# S5 pass 2: waves 4-7 start half a token group late so their VALU phases overlap the partner wave's f32 MFMA phase
# baseline (speedup 1.0000x reference)
.LBB0_290:
	s_or_b64 exec, exec, s[18:19]
	v_mov_b32_e32 v75, v199
	v_lshl_add_u64 v[36:37], v[88:89], 0, v[74:75]
	global_load_dwordx4 v[40:43], v[90:91], off
	global_load_dwordx2 v[92:93], v[36:37], off
	s_lshl_b32 s52, s22, 1
	v_lshl_add_u64 v[76:77], v[60:61], 0, s[52:53]
	v_lshl_add_u64 v[86:87], v[70:71], 0, v[86:87]
	s_mov_b64 s[18:19], 0
	v_xor_b32_e32 v75, 0x80000000, v114
	v_xor_b32_e32 v114, 0x80000000, v115
	v_xor_b32_e32 v115, 0x80000000, v116
	v_xor_b32_e32 v116, 0x80000000, v117
	v_xor_b32_e32 v117, 0x80000000, v118
	v_xor_b32_e32 v118, 0x80000000, v119
	v_xor_b32_e32 v119, 0x80000000, v120
	v_xor_b32_e32 v120, 0x80000000, v121
	v_xor_b32_e32 v121, 0x80000000, v122
	v_xor_b32_e32 v122, 0x80000000, v123
	v_xor_b32_e32 v123, 0x80000000, v124
	v_xor_b32_e32 v124, 0x80000000, v125
	v_xor_b32_e32 v125, 0x80000000, v126
	v_xor_b32_e32 v126, 0x80000000, v127
	v_xor_b32_e32 v127, 0x80000000, v128
	v_xor_b32_e32 v128, 0x80000000, v129
	v_mov_b64_e32 v[88:89], v[46:47]
	s_waitcnt vmcnt(1)
	v_mov_b64_e32 v[36:37], v[40:41]
	s_waitcnt vmcnt(0)
	v_mov_b64_e32 v[90:91], v[92:93]
	v_mov_b64_e32 v[38:39], v[42:43]
	v_readfirstlane_b32 s0, v238
	s_nop 1
	s_cmpk_lt_u32 s0, 0x100
	s_cbranch_scc1 .Ls5_pass2_go
	s_sleep 20
.Ls5_pass2_go:
	s_branch .LBB0_292
.LBB0_291:
	v_mfma_f32_16x16x32_bf16 v[144:147], v[40:43], v[0:3], 0
	s_mov_b32 s0, 0xbf3a00e3
	s_add_u32 s18, s18, 0x28000
	s_addc_u32 s19, s19, 0
	v_mfma_f32_16x16x32_bf16 v[148:151], v[40:43], v[8:11], 0
	s_nop 7
	ds_write2_b32 v97, v144, v148 offset1:16
	ds_write2_b32 v97, v145, v149 offset0:130 offset1:146
	ds_write2_b32 v73, v146, v150 offset0:4 offset1:20
	v_mfma_f32_16x16x32_bf16 v[152:155], v[40:43], v[16:19], 0
	s_cmp_eq_u32 s18, 0x280000
	v_mfma_f32_16x16x32_bf16 v[156:159], v[40:43], v[24:27], 0
	ds_write2_b32 v73, v147, v151 offset0:134 offset1:150
	s_nop 6
	ds_write2_b32 v97, v152, v156 offset0:32 offset1:48
	ds_write2_b32 v97, v153, v157 offset0:162 offset1:178
	v_mfma_f32_16x16x32_bf16 v[160:163], v[40:43], v[4:7], 0
	v_mfma_f32_16x16x32_bf16 v[144:147], v[40:43], v[12:15], 0
	ds_write2_b32 v73, v154, v158 offset0:36 offset1:52
	ds_write2_b32 v73, v155, v159 offset0:166 offset1:182
	s_nop 5
	ds_write2_b32 v97, v160, v144 offset0:64 offset1:80
	ds_write2_b32 v97, v161, v145 offset0:194 offset1:210
	ds_write2_b32 v73, v162, v146 offset0:68 offset1:84
	ds_write2_b32 v73, v163, v147 offset0:198 offset1:214
	v_mfma_f32_16x16x32_bf16 v[148:151], v[40:43], v[20:23], 0
	v_xor_b32_e32 v144, 0x80000000, v95
	v_mov_b32_e32 v145, v94
	v_mfma_f32_16x16x32_bf16 v[40:43], v[40:43], v[28:31], 0
	s_nop 7
	ds_write2_b32 v97, v148, v40 offset0:96 offset1:112
	ds_write2_b32 v97, v149, v41 offset0:226 offset1:242
	ds_write2_b32 v73, v150, v42 offset0:100 offset1:116
	ds_write2_b32 v73, v151, v43 offset0:230 offset1:246
	s_waitcnt lgkmcnt(0)
	ds_read2st64_b32 v[164:165], v63 offset1:1
	ds_read2_b32 v[166:167], v63 offset0:130 offset1:194
	ds_read2st64_b32 v[168:169], v130 offset0:4 offset1:5
	ds_read2st64_b32 v[170:171], v131 offset0:6 offset1:7
	ds_read2st64_b32 v[172:173], v132 offset0:8 offset1:9
	ds_read2st64_b32 v[174:175], v133 offset0:10 offset1:11
	ds_read2st64_b32 v[176:177], v134 offset0:12 offset1:13
	ds_read2st64_b32 v[178:179], v135 offset0:14 offset1:15
	ds_read2st64_b32 v[180:181], v136 offset0:16 offset1:17
	ds_read2st64_b32 v[182:183], v137 offset0:18 offset1:19
	ds_read2st64_b32 v[184:185], v138 offset0:20 offset1:21
	ds_read2st64_b32 v[186:187], v139 offset0:22 offset1:23
	ds_read2st64_b32 v[188:189], v140 offset0:24 offset1:25
	ds_read2st64_b32 v[190:191], v141 offset0:26 offset1:27
	ds_read2st64_b32 v[192:193], v142 offset0:28 offset1:29
	s_waitcnt lgkmcnt(14)
	v_pk_fma_f32 v[42:43], v[80:81], v[94:95], v[164:165]
	ds_read2st64_b32 v[194:195], v143 offset0:30 offset1:31
	s_nop 0
	v_pk_fma_f32 v[164:165], v[82:83], v[144:145], v[42:43]
	s_waitcnt lgkmcnt(14)
	v_pk_fma_f32 v[42:43], v[80:81], v[164:165], v[166:167]
	v_xor_b32_e32 v144, 0x80000000, v165
	v_mov_b32_e32 v145, v164
	v_pk_fma_f32 v[166:167], v[82:83], v[144:145], v[42:43]
	s_waitcnt lgkmcnt(13)
	v_pk_fma_f32 v[42:43], v[80:81], v[166:167], v[168:169]
	v_xor_b32_e32 v144, 0x80000000, v167
	v_mov_b32_e32 v145, v166
	v_pk_fma_f32 v[168:169], v[82:83], v[144:145], v[42:43]
	s_waitcnt lgkmcnt(12)
	v_pk_fma_f32 v[42:43], v[80:81], v[168:169], v[170:171]
	v_xor_b32_e32 v144, 0x80000000, v169
	v_mov_b32_e32 v145, v168
	v_pk_fma_f32 v[170:171], v[82:83], v[144:145], v[42:43]
	s_waitcnt lgkmcnt(11)
	v_pk_fma_f32 v[42:43], v[80:81], v[170:171], v[172:173]
	v_xor_b32_e32 v144, 0x80000000, v171
	v_mov_b32_e32 v145, v170
	v_pk_fma_f32 v[172:173], v[82:83], v[144:145], v[42:43]
	s_waitcnt lgkmcnt(10)
	v_pk_fma_f32 v[42:43], v[80:81], v[172:173], v[174:175]
	v_xor_b32_e32 v144, 0x80000000, v173
	v_mov_b32_e32 v145, v172
	v_pk_fma_f32 v[174:175], v[82:83], v[144:145], v[42:43]
	s_waitcnt lgkmcnt(9)
	v_pk_fma_f32 v[42:43], v[80:81], v[174:175], v[176:177]
	v_xor_b32_e32 v144, 0x80000000, v175
	v_mov_b32_e32 v145, v174
	v_pk_fma_f32 v[176:177], v[82:83], v[144:145], v[42:43]
	s_waitcnt lgkmcnt(8)
	v_pk_fma_f32 v[42:43], v[80:81], v[176:177], v[178:179]
	v_xor_b32_e32 v144, 0x80000000, v177
	v_mov_b32_e32 v145, v176
	v_pk_fma_f32 v[178:179], v[82:83], v[144:145], v[42:43]
	s_waitcnt lgkmcnt(7)
	v_pk_fma_f32 v[42:43], v[80:81], v[178:179], v[180:181]
	v_xor_b32_e32 v144, 0x80000000, v179
	v_mov_b32_e32 v145, v178
	v_pk_fma_f32 v[180:181], v[82:83], v[144:145], v[42:43]
	s_waitcnt lgkmcnt(6)
	v_pk_fma_f32 v[42:43], v[80:81], v[180:181], v[182:183]
	v_xor_b32_e32 v144, 0x80000000, v181
	v_mov_b32_e32 v145, v180
	v_pk_fma_f32 v[182:183], v[82:83], v[144:145], v[42:43]
	s_waitcnt lgkmcnt(5)
	v_pk_fma_f32 v[42:43], v[80:81], v[182:183], v[184:185]
	v_xor_b32_e32 v144, 0x80000000, v183
	v_mov_b32_e32 v145, v182
	v_pk_fma_f32 v[184:185], v[82:83], v[144:145], v[42:43]
	s_waitcnt lgkmcnt(4)
	v_pk_fma_f32 v[42:43], v[80:81], v[184:185], v[186:187]
	v_xor_b32_e32 v144, 0x80000000, v185
	v_mov_b32_e32 v145, v184
	v_pk_fma_f32 v[186:187], v[82:83], v[144:145], v[42:43]
	s_waitcnt lgkmcnt(3)
	v_pk_fma_f32 v[42:43], v[80:81], v[186:187], v[188:189]
	v_xor_b32_e32 v144, 0x80000000, v187
	v_mov_b32_e32 v145, v186
	v_pk_fma_f32 v[188:189], v[82:83], v[144:145], v[42:43]
	s_waitcnt lgkmcnt(2)
	v_pk_fma_f32 v[42:43], v[80:81], v[188:189], v[190:191]
	v_xor_b32_e32 v144, 0x80000000, v189
	v_mov_b32_e32 v145, v188
	v_pk_fma_f32 v[190:191], v[82:83], v[144:145], v[42:43]
	s_waitcnt lgkmcnt(1)
	v_pk_fma_f32 v[42:43], v[80:81], v[190:191], v[192:193]
	v_xor_b32_e32 v144, 0x80000000, v191
	v_mov_b32_e32 v145, v190
	v_pk_fma_f32 v[192:193], v[82:83], v[144:145], v[42:43]
	s_waitcnt lgkmcnt(0)
	v_pk_fma_f32 v[42:43], v[80:81], v[192:193], v[194:195]
	v_xor_b32_e32 v144, 0x80000000, v193
	v_mov_b32_e32 v145, v192
	v_pk_fma_f32 v[94:95], v[82:83], v[144:145], v[42:43]
	ds_write2st64_b32 v63, v164, v165 offset1:1
	ds_write2_b32 v63, v166, v167 offset0:130 offset1:194
	ds_write2st64_b32 v130, v168, v169 offset0:4 offset1:5
	ds_write2st64_b32 v131, v170, v171 offset0:6 offset1:7
	ds_write2st64_b32 v132, v172, v173 offset0:8 offset1:9
	ds_write2st64_b32 v133, v174, v175 offset0:10 offset1:11
	ds_write2st64_b32 v134, v176, v177 offset0:12 offset1:13
	ds_write2st64_b32 v135, v178, v179 offset0:14 offset1:15
	ds_write2st64_b32 v136, v180, v181 offset0:16 offset1:17
	ds_write2st64_b32 v137, v182, v183 offset0:18 offset1:19
	ds_write2st64_b32 v138, v184, v185 offset0:20 offset1:21
	ds_write2st64_b32 v139, v186, v187 offset0:22 offset1:23
	ds_write2st64_b32 v140, v188, v189 offset0:24 offset1:25
	ds_write2st64_b32 v141, v190, v191 offset0:26 offset1:27
	ds_write2st64_b32 v142, v192, v193 offset0:28 offset1:29
	ds_write2st64_b32 v143, v94, v95 offset0:30 offset1:31
	s_waitcnt lgkmcnt(0)
	ds_read2_b32 v[164:165], v96 offset0:0 offset1:4
	ds_read2_b32 v[166:167], v96 offset0:8 offset1:12
	ds_read2_b32 v[168:169], v96 offset0:16 offset1:20
	ds_read2_b32 v[170:171], v96 offset0:24 offset1:28
	ds_read2_b32 v[172:173], v96 offset0:32 offset1:36
	ds_read2_b32 v[174:175], v96 offset0:40 offset1:44
	ds_read2_b32 v[176:177], v96 offset0:48 offset1:52
	ds_read2_b32 v[178:179], v96 offset0:56 offset1:60
	ds_read2_b32 v[180:181], v96 offset0:64 offset1:68
	ds_read2_b32 v[182:183], v96 offset0:72 offset1:76
	ds_read2_b32 v[184:185], v96 offset0:80 offset1:84
	ds_read2_b32 v[186:187], v96 offset0:88 offset1:92
	ds_read2_b32 v[188:189], v96 offset0:96 offset1:100
	ds_read2_b32 v[190:191], v96 offset0:104 offset1:108
	ds_read2_b32 v[192:193], v96 offset0:112 offset1:116
	s_nop 0
	s_nop 0
	s_waitcnt lgkmcnt(14)
	v_mfma_f32_16x16x4_f32 v[40:43], v98, v164, 0
	ds_read2_b32 v[194:195], v96 offset0:120 offset1:124
	s_nop 0
	s_nop 0
	v_mfma_f32_16x16x4_f32 v[144:147], v99, v165, 0
	s_nop 0
	s_waitcnt lgkmcnt(14)
	v_mfma_f32_16x16x4_f32 v[148:151], v100, v166, 0
	v_mfma_f32_16x16x4_f32 v[152:155], v101, v167, 0
	s_nop 0
	s_waitcnt lgkmcnt(13)
	v_mfma_f32_16x16x4_f32 v[40:43], v102, v168, v[40:43]
	v_mfma_f32_16x16x4_f32 v[144:147], v103, v169, v[144:147]
	s_nop 0
	s_nop 0
	s_waitcnt lgkmcnt(12)
	v_mfma_f32_16x16x4_f32 v[148:151], v104, v170, v[148:151]
	v_mfma_f32_16x16x4_f32 v[152:155], v105, v171, v[152:155]
	s_nop 0
	s_nop 0
	s_waitcnt lgkmcnt(11)
	v_mfma_f32_16x16x4_f32 v[40:43], v106, v172, v[40:43]
	v_mfma_f32_16x16x4_f32 v[144:147], v107, v173, v[144:147]
	s_nop 0
	s_nop 0
	s_waitcnt lgkmcnt(10)
	v_mfma_f32_16x16x4_f32 v[148:151], v108, v174, v[148:151]
	v_mfma_f32_16x16x4_f32 v[152:155], v109, v175, v[152:155]
	s_nop 0
	s_nop 0
	s_waitcnt lgkmcnt(9)
	v_mfma_f32_16x16x4_f32 v[40:43], v110, v176, v[40:43]
	v_mfma_f32_16x16x4_f32 v[144:147], v111, v177, v[144:147]
	s_nop 0
	s_nop 0
	s_waitcnt lgkmcnt(8)
	v_mfma_f32_16x16x4_f32 v[148:151], v112, v178, v[148:151]
	v_mfma_f32_16x16x4_f32 v[152:155], v113, v179, v[152:155]
	s_nop 0
	s_nop 0
	s_waitcnt lgkmcnt(7)
	v_mfma_f32_16x16x4_f32 v[40:43], v75, v180, v[40:43]
	v_mfma_f32_16x16x4_f32 v[144:147], v114, v181, v[144:147]
	s_nop 0
	s_nop 0
	s_waitcnt lgkmcnt(6)
	v_mfma_f32_16x16x4_f32 v[148:151], v115, v182, v[148:151]
	v_mfma_f32_16x16x4_f32 v[152:155], v116, v183, v[152:155]
	s_nop 0
	s_nop 0
	s_waitcnt lgkmcnt(5)
	v_mfma_f32_16x16x4_f32 v[40:43], v117, v184, v[40:43]
	v_mfma_f32_16x16x4_f32 v[144:147], v118, v185, v[144:147]
	s_nop 0
	s_nop 0
	s_waitcnt lgkmcnt(4)
	v_mfma_f32_16x16x4_f32 v[148:151], v119, v186, v[148:151]
	v_mfma_f32_16x16x4_f32 v[152:155], v120, v187, v[152:155]
	s_nop 0
	s_nop 0
	s_waitcnt lgkmcnt(3)
	v_mfma_f32_16x16x4_f32 v[40:43], v121, v188, v[40:43]
	v_mfma_f32_16x16x4_f32 v[144:147], v122, v189, v[144:147]
	s_nop 0
	s_nop 0
	s_waitcnt lgkmcnt(2)
	v_mfma_f32_16x16x4_f32 v[148:151], v123, v190, v[148:151]
	v_mfma_f32_16x16x4_f32 v[152:155], v124, v191, v[152:155]
	s_nop 0
	s_nop 0
	s_waitcnt lgkmcnt(1)
	v_mfma_f32_16x16x4_f32 v[40:43], v125, v192, v[40:43]
	v_mfma_f32_16x16x4_f32 v[144:147], v126, v193, v[144:147]
	s_nop 0
	s_nop 0
	s_waitcnt lgkmcnt(0)
	v_mfma_f32_16x16x4_f32 v[148:151], v127, v194, v[148:151]
	s_nop 6
	v_add_f32_e64 v146, v42, v146
	v_add_f32_e64 v147, v43, v147
	v_add_f32_e64 v144, v40, v144
	v_add_f32_e64 v145, v41, v145
	v_mfma_f32_16x16x4_f32 v[40:43], v128, v195, v[152:155]
	s_nop 9
	v_pk_add_f32 v[40:41], v[148:149], v[40:41]
	v_pk_add_f32 v[42:43], v[150:151], v[42:43]
	v_pk_add_f32 v[40:41], v[144:145], v[40:41]
	v_lshlrev_b32_e32 v144, 16, v92
	v_and_b32_e32 v145, 0xffff0000, v92
	v_pk_fma_f32 v[40:41], v[32:33], v[144:145], v[40:41]
	v_pk_add_f32 v[42:43], v[146:147], v[42:43]
	v_fma_f32 v92, |v40|, s57, 1.0
	v_rcp_f32_e32 v144, v92
	v_fma_f32 v92, |v41|, s57, 1.0
	v_rcp_f32_e32 v145, v92
	v_pk_mul_f32 v[146:147], v[40:41], v[40:41]
	v_mov_b64_e32 v[148:149], s[0:1]
	v_mul_f32_e32 v92, 0xbf38aa3b, v146
	v_exp_f32_e32 v146, v92
	v_pk_fma_f32 v[150:151], v[144:145], s[60:61], v[148:149] op_sel_hi:[1,0,0]
	v_mul_f32_e32 v92, 0xbf38aa3b, v147
	v_pk_fma_f32 v[150:151], v[144:145], v[150:151], s[62:63] op_sel_hi:[1,1,0]
	v_exp_f32_e32 v147, v92
	v_pk_fma_f32 v[150:151], v[144:145], v[150:151], s[64:65] op_sel_hi:[1,1,0]
	v_cmp_gt_f32_e32 vcc, 0, v41
	v_pk_fma_f32 v[150:151], v[144:145], v[150:151], s[66:67] op_sel_hi:[1,1,0]
	s_nop 0
	v_pk_mul_f32 v[144:145], v[144:145], v[150:151]
	s_nop 0
	v_pk_mul_f32 v[144:145], v[146:147], v[144:145]
	s_nop 0
	v_pk_mul_f32 v[146:147], v[40:41], v[144:145]
	v_pk_fma_f32 v[144:145], v[40:41], v[144:145], v[40:41] neg_lo:[1,0,0] neg_hi:[1,0,0]
	v_and_b32_e32 v41, 0xffff0000, v93
	v_cndmask_b32_e32 v129, v145, v147, vcc
	v_cmp_gt_f32_e32 vcc, 0, v40
	v_lshlrev_b32_e32 v40, 16, v93
	v_pk_fma_f32 v[40:41], v[34:35], v[40:41], v[42:43]
	v_cndmask_b32_e32 v146, v144, v146, vcc
	v_fma_f32 v42, |v40|, s57, 1.0
	v_fma_f32 v43, |v41|, s57, 1.0
	v_rcp_f32_e32 v42, v42
	v_rcp_f32_e32 v43, v43
	v_pk_mul_f32 v[92:93], v[40:41], v[40:41]
	v_cmp_gt_f32_e32 vcc, 0, v41
	v_mul_f32_e32 v92, 0xbf38aa3b, v92
	v_pk_fma_f32 v[144:145], v[42:43], s[60:61], v[148:149] op_sel_hi:[1,0,0]
	v_mul_f32_e32 v93, 0xbf38aa3b, v93
	v_exp_f32_e32 v92, v92
	v_pk_fma_f32 v[144:145], v[42:43], v[144:145], s[62:63] op_sel_hi:[1,1,0]
	v_exp_f32_e32 v93, v93
	v_pk_fma_f32 v[144:145], v[42:43], v[144:145], s[64:65] op_sel_hi:[1,1,0]
	s_nop 0
	v_pk_fma_f32 v[144:145], v[42:43], v[144:145], s[66:67] op_sel_hi:[1,1,0]
	s_nop 0
	v_pk_mul_f32 v[42:43], v[42:43], v[144:145]
	s_nop 0
	v_pk_mul_f32 v[42:43], v[92:93], v[42:43]
	s_nop 0
	v_pk_mul_f32 v[92:93], v[40:41], v[42:43]
	v_pk_fma_f32 v[42:43], v[40:41], v[42:43], v[40:41] neg_lo:[1,0,0] neg_hi:[1,0,0]
	s_nop 0
	v_cndmask_b32_e32 v41, v43, v93, vcc
	v_cmp_gt_f32_e32 vcc, 0, v40
	v_or_b32_e32 v43, v79, v89
	v_cvt_pk_bf16_f32 v40, v146, v129
	v_cndmask_b32_e32 v42, v42, v92, vcc
	v_cvt_pk_bf16_f32 v41, v42, v41
	v_or_b32_e32 v42, v78, v88
	v_lshlrev_b64 v[42:43], 10, v[42:43]
	v_lshl_add_u64 v[42:43], v[76:77], 0, v[42:43]
	global_store_dwordx2 v[42:43], v[40:41], off
	s_waitcnt lgkmcnt(0)
	s_waitcnt vmcnt(2)
	v_mov_b64_e32 v[42:43], v[38:39]
	v_lshl_add_u64 v[88:89], v[88:89], 0, 16
	v_mov_b64_e32 v[40:41], v[36:37]
	s_waitcnt vmcnt(1)
	v_mov_b64_e32 v[92:93], v[90:91]
	s_cbranch_scc1 .LBB0_275
